# unroll silu(c) load loop in prep and conv-tap LDS fill loop: loads issued together, one counted wait
# speedup vs baseline: 1.0003x; 1.0003x over previous
; #define LAS __attribute__((address_space(3)))
; __device__ __forceinline__ float siluf_(float x) { return x * sigmoidf_(x); }
; __device__ __forceinline__ void prep_mod(Frame& F) {
;     ...
;         for (int e = tid; e < 3 * D; e += 512) { const int rho = e >> 10, k = e & 1023; const float v = rho < 2 ? F.in[I_C][rho * D + k] : F.in[I_CCTX][k]; sc[e] = siluf_(v); }
;         __syncthreads();
;         LAS float* red = fl + 3 * D;
;         for (int item = F.bid; item < 2 * 96; item += F.G) {
;             const int layer = item / 96, n0 = (item % 96) * 32, kk = tid >> 5, nn = tid & 31;
; __global__ void __launch_bounds__(512, 2) mk_fwd(Args args) {
;     ...
;     F.tid = threadIdx.x; F.lane = F.tid & 63; F.wave = __builtin_amdgcn_readfirstlane(F.tid >> 6); F.G = gridDim.x; F.bid = blockIdx.x;
; #pragma unroll
;     for (int i = 0; i < 23; ++i) F.in[i] = args.in[i];
;     F.out = args.out; F.ws = args.ws;
;     volatile LAS unsigned* MISC = (volatile LAS unsigned*)(F.lds + MISC_OFF);
;     if (F.tid < 32) MISC[F.tid] = 0u;
;     __syncthreads();
;     XcdBarrier bar; bar.bar = (unsigned*)(F.ws + WS_CTL) + CW_BAR; bar.x = 0; bar.st = nullptr;
;     ...
;     const int lo = args.ph_lo, hi = args.ph_hi;
.LBB0_5:
	s_or_b64 exec, exec, s[4:5]
	s_load_dwordx16 s[36:51], s[0:1], 0x0
	s_load_dwordx16 s[68:83], s[0:1], 0x40
	s_load_dwordx2 s[26:27], s[0:1], 0xc8
	s_load_dwordx16 s[4:19], s[0:1], 0x80
	s_lshr_b32 s0, s86, 6
	v_and_b32_e32 v209, 63, v0
	s_waitcnt lgkmcnt(0)
	v_writelane_b32 v253, s4, 7
	s_nop 1
	v_writelane_b32 v253, s5, 8
	v_writelane_b32 v253, s6, 9
	v_writelane_b32 v253, s7, 10
	v_writelane_b32 v253, s8, 11
	v_writelane_b32 v253, s9, 12
	v_writelane_b32 v253, s10, 13
	v_writelane_b32 v253, s11, 14
	v_writelane_b32 v253, s12, 15
	v_writelane_b32 v253, s13, 16
	v_writelane_b32 v253, s14, 17
	v_writelane_b32 v253, s15, 18
	v_writelane_b32 v253, s16, 19
	v_writelane_b32 v253, s17, 20
	v_writelane_b32 v253, s18, 21
	v_writelane_b32 v253, s19, 22
	v_writelane_b32 v253, s0, 23
	s_add_u32 s0, s56, 0x100000
	s_addc_u32 s1, s57, 0
	v_writelane_b32 v253, s0, 24
	s_cmp_lt_i32 s26, 1
	s_nop 0
	v_writelane_b32 v253, s1, 25
	v_writelane_b32 v253, s36, 26
	s_cselect_b64 s[0:1], -1, 0
	s_cmp_gt_i32 s27, 0
	v_writelane_b32 v253, s37, 27
	v_writelane_b32 v253, s38, 28
	v_writelane_b32 v253, s39, 29
	v_writelane_b32 v253, s40, 30
	v_writelane_b32 v253, s41, 31
	v_writelane_b32 v253, s42, 32
	v_writelane_b32 v253, s43, 33
	v_writelane_b32 v253, s44, 34
	v_writelane_b32 v253, s45, 35
	v_writelane_b32 v253, s46, 36
	v_writelane_b32 v253, s47, 37
	v_writelane_b32 v253, s48, 38
	v_writelane_b32 v253, s49, 39
	s_cselect_b64 s[2:3], -1, 0
	v_writelane_b32 v253, s50, 40
	s_and_b64 s[0:1], s[0:1], s[2:3]
	v_writelane_b32 v253, s51, 41
	s_andn2_b64 vcc, exec, s[0:1]
	v_writelane_b32 v253, s26, 42
	s_nop 1
	v_writelane_b32 v253, s27, 43
	s_cbranch_vccnz .LBB0_72
	v_mov_b32_e32 v5, 0
	v_lshlrev_b32_e32 v2, 2, v0
	v_mov_b32_e32 v3, v5
	v_lshl_add_u64 v[6:7], s[38:39], 0, v[2:3]
	v_lshl_add_u64 v[14:15], s[42:43], 0, v[2:3]
	s_mov_b64 s[4:5], 0x1000
	v_lshl_add_u64 v[10:11], v[6:7], 0, s[4:5]
	v_add_u32_e32 v1, 0, v2
	global_load_dword v8, v[6:7], off
	global_load_dword v9, v[6:7], off offset:2048
	global_load_dword v12, v[10:11], off
	global_load_dword v13, v[10:11], off offset:2048
	global_load_dword v16, v[14:15], off
	global_load_dword v17, v[14:15], off offset:2048
	s_waitcnt vmcnt(4)
	v_mul_f32_e32 v18, 0xbfb8aa3b, v8
	v_mul_f32_e32 v19, 0xbfb8aa3b, v9
	v_exp_f32_e32 v18, v18
	v_exp_f32_e32 v19, v19
	s_nop 0
	v_add_f32_e32 v18, 1.0, v18
	v_add_f32_e32 v19, 1.0, v19
	v_rcp_f32_e32 v18, v18
	v_rcp_f32_e32 v19, v19
	s_nop 0
	v_mul_f32_e32 v8, v8, v18
	v_mul_f32_e32 v9, v9, v19
	ds_write_b32 v1, v8
	ds_write_b32 v1, v9 offset:2048
	s_waitcnt vmcnt(2)
	v_mul_f32_e32 v18, 0xbfb8aa3b, v12
	v_mul_f32_e32 v19, 0xbfb8aa3b, v13
	v_exp_f32_e32 v18, v18
	v_exp_f32_e32 v19, v19
	s_nop 0
	v_add_f32_e32 v18, 1.0, v18
	v_add_f32_e32 v19, 1.0, v19
	v_rcp_f32_e32 v18, v18
	v_rcp_f32_e32 v19, v19
	s_nop 0
	v_mul_f32_e32 v12, v12, v18
	v_mul_f32_e32 v13, v13, v19
	ds_write_b32 v1, v12 offset:4096
	ds_write_b32 v1, v13 offset:6144
	s_waitcnt vmcnt(0)
	v_mul_f32_e32 v18, 0xbfb8aa3b, v16
	v_mul_f32_e32 v19, 0xbfb8aa3b, v17
	v_exp_f32_e32 v18, v18
	v_exp_f32_e32 v19, v19
	s_nop 0
	v_add_f32_e32 v18, 1.0, v18
	v_add_f32_e32 v19, 1.0, v19
	v_rcp_f32_e32 v18, v18
	v_rcp_f32_e32 v19, v19
	s_nop 0
	v_mul_f32_e32 v16, v16, v18
	v_mul_f32_e32 v17, v17, v19
	ds_write_b32 v1, v16 offset:8192
	ds_write_b32 v1, v17 offset:10240
	s_cmpk_lt_i32 s92, 0xc0
	s_cselect_b64 s[6:7], -1, 0
	s_cmpk_gt_i32 s92, 0xbf
	s_waitcnt lgkmcnt(0)
	s_barrier
	s_cbranch_scc1 .LBB0_15
	v_lshrrev_b32_e32 v3, 5, v0
	v_lshrrev_b32_e32 v4, 5, v0
	v_and_b32_e32 v6, 31, v0
	v_mul_hi_u32_u24_e32 v11, 0x3000, v3
	v_mul_u32_u24_e32 v3, 0x3000, v3
	v_mul_u32_u24_e32 v5, 12, v0
	s_movk_i32 s0, 0x60
	v_lshl_add_u32 v1, v4, 2, 0
	v_mul_u32_u24_e32 v7, 12, v6
	v_lshl_or_b32 v10, v6, 2, v3
	v_mov_b32_e32 v9, 0
	v_cmp_gt_u32_e64 s[0:1], s0, v0
	v_lshl_add_u64 v[10:11], s[44:45], 0, v[10:11]
	v_or_b32_e32 v3, 0xffffff00, v4
	s_mov_b64 s[8:9], 0x300000
	s_movk_i32 s2, 0x2ff
	v_add_u32_e32 v5, 0, v5
	v_add_u32_e32 v7, v1, v7
	s_movk_i32 s3, 0xc00
	s_mov_b32 s14, s92
	s_branch .LBB0_11

; #define LAS __attribute__((address_space(3)))
; #define REP(k) for (int rep_ = 0; rep_ < 1 + ((k) == PROBE_REP_PHASE ? PROBE_REP_N : 0); ++rep_)
; #define SEAM(k) do { if (IN(k) && IN((k) + 1)) xcd_barrier(bar); if ((k) + 1 == PROBE_T_LO) pt0 = __builtin_amdgcn_s_memrealtime(); if ((k) == PROBE_T_HI) pt1 = __builtin_amdgcn_s_memrealtime(); } while (0)
; __global__ void __launch_bounds__(512, 2) mk_fwd(Args args) {
;     ...
;         if (IN(2)) { LAS float* cwl = (LAS float*)(F.lds + CWL_OFF); for (int e = F.tid; e < 3 * 2048; e += 512) cwl[e] = F.in[I_CW][e]; } } SEAM(1);
;     if (IN(2)) REP(2) { if (!IN(1)) { LAS float* cwl = (LAS float*)(F.lds + CWL_OFF); for (int e = F.tid; e < 3 * 2048; e += 512) cwl[e] = F.in[I_CW][e]; __syncthreads(); } g8::ProbG1 p{(const char*)ws + WS_HX, (const char*)F.out, (const char*)ws + WS_W1, F.in[I_CW], (char*)ws + WS_A2}; run_gemm(F, p, 0);
.LBB0_97:
	s_cmp_lt_u32 s27, 3
	s_cbranch_scc1 .LBB0_101
	v_lshlrev_b32_e32 v4, 2, v0
	v_mov_b32_e32 v5, 0
	v_lshl_add_u64 v[2:3], s[70:71], 0, v[4:5]
	v_add_u32_e32 v4, 0, v4
	v_add_u32_e32 v4, 0x20800, v4
	s_mov_b64 s[8:9], 0x1000
	global_load_dword v6, v[2:3], off
	global_load_dword v7, v[2:3], off offset:2048
	v_lshl_add_u64 v[2:3], v[2:3], 0, s[8:9]
	global_load_dword v8, v[2:3], off
	global_load_dword v9, v[2:3], off offset:2048
	v_lshl_add_u64 v[2:3], v[2:3], 0, s[8:9]
	global_load_dword v10, v[2:3], off
	global_load_dword v11, v[2:3], off offset:2048
	v_lshl_add_u64 v[2:3], v[2:3], 0, s[8:9]
	global_load_dword v12, v[2:3], off
	global_load_dword v13, v[2:3], off offset:2048
	v_lshl_add_u64 v[2:3], v[2:3], 0, s[8:9]
	global_load_dword v14, v[2:3], off
	global_load_dword v15, v[2:3], off offset:2048
	v_lshl_add_u64 v[2:3], v[2:3], 0, s[8:9]
	global_load_dword v16, v[2:3], off
	global_load_dword v17, v[2:3], off offset:2048
	s_waitcnt vmcnt(11)
	ds_write_b32 v4, v6
	s_waitcnt vmcnt(10)
	ds_write_b32 v4, v7 offset:2048
	s_waitcnt vmcnt(9)
	ds_write_b32 v4, v8 offset:4096
	s_waitcnt vmcnt(8)
	ds_write_b32 v4, v9 offset:6144
	s_waitcnt vmcnt(7)
	ds_write_b32 v4, v10 offset:8192
	s_waitcnt vmcnt(6)
	ds_write_b32 v4, v11 offset:10240
	s_waitcnt vmcnt(5)
	ds_write_b32 v4, v12 offset:12288
	s_waitcnt vmcnt(4)
	ds_write_b32 v4, v13 offset:14336
	s_waitcnt vmcnt(3)
	ds_write_b32 v4, v14 offset:16384
	s_waitcnt vmcnt(2)
	ds_write_b32 v4, v15 offset:18432
	s_waitcnt vmcnt(1)
	ds_write_b32 v4, v16 offset:20480
	s_waitcnt vmcnt(0)
	ds_write_b32 v4, v17 offset:22528
